# static s_setprio 1 for waves 4-7 during the attention phase (strategy 7.4), reset at phase exit
# speedup vs baseline: 1.0005x; 1.0005x over previous
; #define OPQ_V(x) asm volatile("" : "+v"(x))
; __device__ __forceinline__ int t5_bucket(int d) {
;     if (d < 16) return d;
;     int b = 16;
;     b += (d >= 19) + (d >= 21) + (d >= 24) + (d >= 27) + (d >= 31) + (d >= 35) + (d >= 40) + (d >= 46) + (d >= 52) + (d >= 59) + (d >= 67) + (d >= 77) + (d >= 87) + (d >= 99) + (d >= 113);
;     return b;
; __device__ __forceinline__ void attn_unit(int bg, int pb, bool build, const bf16* Q, const bf16* KV, const bf16* KCN, const bf16* VCT, const float* GATES, const float* rel_bias, bf16* A, unsigned char* lds) {
;     int tid_ = threadIdx.x; OPQ_V(tid_); const int tid = tid_, lane = tid & 63, w = __builtin_amdgcn_readfirstlane(tid >> 6), qi = lane & 15, q4 = lane >> 4;
;     const int hl = w & 3, half = w >> 2, b = bg >> 2, g = bg & 3, head = g * 4 + hl;
;     const int p0 = pb * 32 + half * 16, t = p0 + qi; const size_t tok = (size_t)b * 2048 + t;
;     float* biasT = (float*)(lds + AL_BIAS); float* impA = (float*)(lds + AL_IMPA); float* impB = (float*)(lds + AL_IMPB); float* impT = (float*)(lds + AL_IMPT); unsigned* selw = (unsigned*)(lds + AL_SELM);
;     const bf16x8 qf0 = *(const bf16x8*)(Q + tok * 1024 + head * 64 + q4 * 8), qf1 = *(const bf16x8*)(Q + tok * 1024 + head * 64 + 32 + q4 * 8);
;     const float g0 = GATES[tok * 48 + head * 3 + 0], g1 = GATES[tok * 48 + head * 3 + 1], g2 = GATES[tok * 48 + head * 3 + 2];
;     if (tid < 32) selw[tid] = 0u;
;     if (build) {
;         const int h_ = tid >> 7, d_ = tid & 127; if (d_ < BIAS_N) biasT[h_ * 128 + d_] = rel_bias[t5_bucket(d_) * 16 + g * 4 + h_] * LOG2E;
.LBB0_241:
	s_lshl_b32 s0, s2, 1
	s_and_b32 s0, s0, 14
	s_bfe_u32 s1, s2, 0x10007
	v_mov_b32_e32 v60, v202
	s_or_b32 s69, s0, s1
	s_lshl_b32 s96, s88, 5
	v_readfirstlane_b32 s0, v60
	s_bfe_u32 s12, s0, 0x20006
	s_ashr_i32 s0, s0, 4
	s_and_b32 s75, s0, -16
	s_cmp_lg_u32 s75, 0
	s_cbranch_scc0 .Lprio_skip
	s_setprio 1
.Lprio_skip:
	v_and_b32_e32 v58, 15, v60
	s_add_i32 s80, s75, s96
	v_or_b32_e32 v126, s80, v58
	s_lshl_b32 s0, s2, 10
	s_lshl_b32 s1, s69, 2
	s_and_b32 s38, s0, 0x1800
	v_ashrrev_i32_e32 v127, 31, v126
	s_and_b32 s11, s1, 12
	v_lshl_add_u64 v[6:7], v[126:127], 0, s[38:39]
	v_readlane_b32 s0, v255, 30
	s_or_b32 s10, s12, s11
	s_waitcnt lgkmcnt(0)
	v_lshlrev_b64 v[2:3], 11, v[6:7]
	v_readlane_b32 s1, v255, 31
	v_bfe_u32 v59, v60, 4, 2
	s_lshl_b32 s38, s10, 7
	v_lshl_add_u64 v[2:3], s[0:1], 0, v[2:3]
	v_lshl_add_u64 v[2:3], v[2:3], 0, s[38:39]
	v_lshlrev_b32_e32 v0, 4, v59
	v_readlane_b32 s0, v255, 36
	v_lshl_add_u64 v[2:3], v[2:3], 0, v[0:1]
	v_readlane_b32 s1, v255, 37
	global_load_dwordx4 v[18:21], v[2:3], off
	global_load_dwordx4 v[22:25], v[2:3], off offset:64
	v_mov_b64_e32 v[2:3], s[0:1]
	s_movk_i32 s7, 0xc0
	v_mad_u64_u32 v[2:3], s[0:1], v6, s7, v[2:3]
	v_mad_i32_i24 v3, v7, s7, v3
	s_mul_i32 s38, s10, 12
	v_lshl_add_u64 v[2:3], v[2:3], 0, s[38:39]
	global_load_dwordx3 v[122:124], v[2:3], off
	v_cmp_gt_i32_e32 vcc, 32, v60
	s_and_saveexec_b64 s[0:1], vcc
	v_lshl_add_u32 v0, v60, 2, 0
	ds_write_b32 v0, v1 offset:38912
	s_or_b64 exec, exec, s[0:1]
	s_cmp_eq_u32 s69, s6
	s_cbranch_scc1 .LBB0_249
	v_and_b32_e32 v0, 0x7f, v60
	s_movk_i32 s0, 0x72
	v_cmp_gt_u32_e32 vcc, s0, v0
	s_and_saveexec_b64 s[0:1], vcc
	s_cbranch_execz .LBB0_248
	v_cmp_lt_u32_e32 vcc, 15, v0
	s_and_saveexec_b64 s[6:7], vcc
	s_cbranch_execz .LBB0_247
	v_cmp_lt_u32_e32 vcc, 18, v0
	s_movk_i32 s13, 0x4c
	s_nop 0
	v_cndmask_b32_e64 v2, 0, 1, vcc
	v_cmp_lt_u32_e32 vcc, 26, v0
	s_nop 1
	v_cndmask_b32_e64 v3, 0, 1, vcc
	v_cmp_lt_u32_e32 vcc, 34, v0
	s_nop 1
	v_cndmask_b32_e64 v4, 0, 1, vcc
	v_cmp_lt_u32_e32 vcc, 45, v0
	s_nop 1
	v_cndmask_b32_e64 v5, 0, 1, vcc
	v_cmp_lt_u32_e32 vcc, 58, v0
	s_nop 1
	v_cndmask_b32_e64 v8, 0, 1, vcc
	v_cmp_lt_u32_e32 vcc, s13, v0
	s_movk_i32 s13, 0x62
	s_nop 0
	v_cndmask_b32_e64 v9, 0, 1, vcc
	v_cmp_lt_u32_e32 vcc, s13, v0
	s_movk_i32 s13, 0x42
	s_nop 0
	v_cndmask_b32_e64 v10, 0, 1, vcc
	v_cmp_lt_u32_e32 vcc, 20, v0
	s_nop 1
	v_cndmask_b32_e64 v11, 16, 17, vcc
	v_cmp_lt_u32_e32 vcc, 23, v0
	s_nop 1
	v_addc_co_u32_e32 v2, vcc, v11, v2, vcc
	v_cmp_lt_u32_e32 vcc, 30, v0
	s_nop 1
	v_addc_co_u32_e32 v2, vcc, v2, v3, vcc
	v_cmp_lt_u32_e32 vcc, 39, v0
	s_nop 1
	v_addc_co_u32_e32 v2, vcc, v2, v4, vcc
	v_cmp_lt_u32_e32 vcc, 51, v0
	s_nop 1
	v_addc_co_u32_e32 v2, vcc, v2, v5, vcc
	v_cmp_lt_u32_e32 vcc, s13, v0
	s_movk_i32 s13, 0x56
	s_nop 0
	v_addc_co_u32_e32 v2, vcc, v2, v8, vcc
	v_cmp_lt_u32_e32 vcc, s13, v0
	s_movk_i32 s13, 0x71
	s_nop 0
	v_addc_co_u32_e32 v2, vcc, v2, v9, vcc
	v_cmp_eq_u32_e32 vcc, s13, v0
	s_nop 1
	v_addc_co_u32_e32 v0, vcc, v2, v10, vcc

; __global__ void __launch_bounds__(512, 2) fwd_megakernel(Args args) {
;     ...
;             }
;             __syncthreads();
.LBB0_648:
	s_setprio 0
	s_waitcnt lgkmcnt(0)
	s_barrier
	s_mov_b64 s[22:23], 0
	v_readlane_b32 s29, v255, 2
	s_movk_i32 s31, 0x2000
	s_mov_b32 s30, 0x38000
	s_movk_i32 s33, 0x4000
